# v54 + dense-GQA attention steps: K-fragment LDS reads issued right after the step barrier, ahead of the two LDS-DMA tile loads
# speedup vs baseline: 1.0160x; 1.0100x over previous
.LBB0_399:
	s_setprio 3
	s_mov_b32 s30, s27
	s_mov_b32 s27, s72
	s_add_i32 s53, s30, 0
	v_add_u32_e32 v0, s53, v126
	ds_read_b128 v[34:37], v0
	ds_read_b128 v[38:41], v0 offset:2048
	s_add_i32 s34, s56, 0xfffc0000
	s_add_i32 s100, s55, -1
	s_and_b32 s34, s34, 0xf00000
	s_and_b32 s100, s100, 3
	s_lshl_b32 s78, s34, 1
	s_add_i32 s54, s29, 0
	s_mul_i32 s58, s100, 0x38000
	s_mov_b32 s59, s79
	s_add_u32 s98, s78, s58
	s_addc_u32 s99, s79, s79
	s_add_i32 s34, s54, s5
	v_lshl_add_u64 v[238:239], v[116:117], 0, s[98:99]
	s_mov_b32 m0, s34
	s_add_i32 s35, s34, 0x2000
	global_load_lds_dwordx4 v[238:239], off
	v_lshl_add_u64 v[238:239], v[118:119], 0, s[98:99]
	s_mov_b32 m0, s35
	s_nop 0
	global_load_lds_dwordx4 v[238:239], off
	v_exp_f32_e32 v145, v66
	v_exp_f32_e32 v146, v67
	v_exp_f32_e32 v147, v68
	v_exp_f32_e32 v148, v69
	v_exp_f32_e32 v149, v70
	v_exp_f32_e32 v150, v71
	v_exp_f32_e32 v151, v72
	s_waitcnt lgkmcnt(0)
	v_mfma_f32_32x32x16_bf16 v[82:97], v[34:37], v[110:113], v[50:65]
	ds_read_b128 v[34:37], v0 offset:4096
	v_exp_f32_e32 v152, v73
	v_exp_f32_e32 v153, v74
	v_exp_f32_e32 v154, v75
	v_exp_f32_e32 v155, v76
	v_exp_f32_e32 v156, v77
	v_exp_f32_e32 v157, v78
	v_mfma_f32_32x32x16_bf16 v[82:97], v[38:41], v[106:109], v[82:97]
	ds_read_b128 v[38:41], v0 offset:6144
	v_exp_f32_e32 v158, v79
	v_exp_f32_e32 v159, v80
	v_exp_f32_e32 v160, v81
	s_waitcnt lgkmcnt(0)
	v_mfma_f32_32x32x16_bf16 v[82:97], v[34:37], v[102:105], v[82:97]
	v_add_f32_e32 v34, v129, v131
	v_add_f32_e32 v66, v132, v34
	ds_read_b128 v[34:37], v0 offset:512
	ds_read_b128 v[42:45], v0 offset:2560
	ds_read_b128 v[46:49], v0 offset:4608
	v_mfma_f32_32x32x16_bf16 v[82:97], v[38:41], v[98:101], v[82:97]
	ds_read_b128 v[38:41], v0 offset:6656
	v_add_f32_e32 v0, v135, v66
	v_add_f32_e32 v0, v136, v0
	v_add_f32_e32 v0, v139, v0
	v_add_f32_e32 v0, v140, v0
	v_add_f32_e32 v0, v143, v0
	v_add_f32_e32 v0, v130, v0
	s_waitcnt lgkmcnt(0)
	v_mfma_f32_32x32x16_bf16 v[66:81], v[34:37], v[110:113], v[50:65]
	v_add_f32_e32 v0, v133, v0
	v_add_f32_e32 v0, v134, v0
	v_add_f32_e32 v0, v137, v0
	v_add_f32_e32 v0, v138, v0
	s_setprio 2
	v_add_f32_e32 v0, v141, v0
	v_add_f32_e32 v0, v142, v0
	v_add_f32_e32 v0, v144, v0
	v_mfma_f32_32x32x16_bf16 v[66:81], v[42:45], v[106:109], v[66:81]
	v_add_f32_e32 v0, v145, v0
	v_add_f32_e32 v0, v146, v0
	v_add_f32_e32 v0, v147, v0
	v_add_f32_e32 v0, v148, v0
	v_add_f32_e32 v0, v149, v0
	v_add_f32_e32 v0, v150, v0
	v_add_f32_e32 v0, v151, v0
	v_mfma_f32_32x32x16_bf16 v[66:81], v[46:49], v[102:105], v[66:81]
	v_add_f32_e32 v0, v152, v0
	v_add_f32_e32 v0, v153, v0
	v_add_f32_e32 v0, v154, v0
	v_add_f32_e32 v0, v155, v0
	v_add_f32_e32 v0, v156, v0
	v_add_f32_e32 v0, v157, v0
	v_add_f32_e32 v0, v158, v0
	v_mfma_f32_32x32x16_bf16 v[66:81], v[38:41], v[98:101], v[66:81]
	v_cvt_pk_bf16_f32 v34, v129, v131
	v_add_f32_e32 v161, v159, v0
	v_cvt_pk_bf16_f32 v35, v132, v135
	v_cvt_pk_bf16_f32 v36, v136, v139
	v_cvt_pk_bf16_f32 v37, v140, v143
	v_cvt_pk_bf16_f32 v38, v130, v133
	v_cvt_pk_bf16_f32 v39, v134, v137
	v_cvt_pk_bf16_f32 v40, v138, v141
	v_cvt_pk_bf16_f32 v41, v142, v144
	v_cvt_pk_bf16_f32 v42, v145, v146
	v_cvt_pk_bf16_f32 v43, v147, v148
	v_cvt_pk_bf16_f32 v44, v149, v150
	v_cvt_pk_bf16_f32 v45, v151, v152
	v_cvt_pk_bf16_f32 v46, v153, v154
	v_cvt_pk_bf16_f32 v47, v155, v156
	v_cvt_pk_bf16_f32 v48, v157, v158
	v_cvt_pk_bf16_f32 v49, v159, v160
	s_add_i32 s57, s72, 0
	v_add_u32_e32 v0, s57, v125
	ds_read_b64_tr_b16 v[130:131], v0 offset:8192
	ds_read_b64_tr_b16 v[132:133], v0 offset:8704
	ds_read_b64_tr_b16 v[134:135], v0 offset:12288
	v_max_f32_e32 v129, v67, v67
	s_waitcnt lgkmcnt(1)
	v_mfma_f32_32x32x16_bf16 v[18:33], v[130:133], v[34:37], v[18:33]
	ds_read_b64_tr_b16 v[136:137], v0 offset:12800
	ds_read_b64_tr_b16 v[130:131], v0 offset:9216
	s_waitcnt lgkmcnt(1)
	v_mfma_f32_32x32x16_bf16 v[2:17], v[134:137], v[34:37], v[2:17]
	ds_read_b64_tr_b16 v[132:133], v0 offset:9728
	ds_read_b64_tr_b16 v[34:35], v0 offset:13312
	s_waitcnt lgkmcnt(1)
	v_mfma_f32_32x32x16_bf16 v[18:33], v[130:133], v[38:41], v[18:33]
	ds_read_b64_tr_b16 v[36:37], v0 offset:13824
	ds_read_b64_tr_b16 v[130:131], v0 offset:10240
	s_waitcnt lgkmcnt(1)
	v_mfma_f32_32x32x16_bf16 v[2:17], v[34:37], v[38:41], v[2:17]
	ds_read_b64_tr_b16 v[132:133], v0 offset:10752
	ds_read_b64_tr_b16 v[34:35], v0 offset:11264
	ds_read_b64_tr_b16 v[36:37], v0 offset:11776
	ds_read_b64_tr_b16 v[38:39], v0 offset:14336
	ds_read_b64_tr_b16 v[40:41], v0 offset:14848
	ds_read_b64_tr_b16 v[134:135], v0 offset:15360
	ds_read_b64_tr_b16 v[136:137], v0 offset:15872
	s_waitcnt lgkmcnt(6)
	v_mfma_f32_32x32x16_bf16 v[18:33], v[130:133], v[42:45], v[18:33]
	v_max_f32_e32 v130, v83, v83
	v_max_f32_e32 v129, v130, v129
	v_max3_f32 v130, v82, v66, v84
	s_setprio 1
	v_max3_f32 v129, v129, v85, v69
	v_max3_f32 v130, v130, v68, v86
	v_max3_f32 v129, v129, v87, v71
	s_waitcnt lgkmcnt(2)
	v_mfma_f32_32x32x16_bf16 v[2:17], v[38:41], v[42:45], v[2:17]
	v_max3_f32 v38, v130, v70, v88
	v_max3_f32 v39, v129, v89, v73
	v_max3_f32 v38, v38, v72, v90
	v_max3_f32 v39, v39, v91, v75
	v_max3_f32 v38, v38, v74, v92
	v_max3_f32 v39, v39, v93, v77
	v_max3_f32 v38, v38, v76, v94
	v_mfma_f32_32x32x16_bf16 v[18:33], v[34:37], v[46:49], v[18:33]
	v_max3_f32 v34, v39, v95, v79
	v_max3_f32 v35, v38, v78, v96
	v_max3_f32 v34, v34, v97, v81
	v_add_f32_e32 v36, v160, v161
	v_max3_f32 v34, v35, v80, v34
	v_add_f32_e32 v128, v128, v36
	v_cmp_lt_f32_e32 vcc, s33, v34
	s_waitcnt lgkmcnt(0)
	v_mfma_f32_32x32x16_bf16 v[2:17], v[134:137], v[46:49], v[2:17]
	s_cbranch_vccz .LBB0_401
	v_mov_b32_e32 v35, v34
	s_nop 1
	v_permlane32_swap_b32 v34, v35
	s_nop 1
	s_nop 0
	v_max3_f32 v36, v34, v35, 0
	v_exp_f32_e64 v38, -v36
	v_add_f32_e32 v127, v127, v36
	v_xor_b32_e32 v34, 0x80000000, v127
	v_pk_add_f32 v[82:83], v[82:83], v[36:37] op_sel_hi:[1,0] neg_lo:[0,1] neg_hi:[0,1]
	v_pk_add_f32 v[66:67], v[66:67], v[36:37] op_sel_hi:[1,0] neg_lo:[0,1] neg_hi:[0,1]
	v_pk_add_f32 v[84:85], v[84:85], v[36:37] op_sel_hi:[1,0] neg_lo:[0,1] neg_hi:[0,1]
	v_pk_add_f32 v[68:69], v[68:69], v[36:37] op_sel_hi:[1,0] neg_lo:[0,1] neg_hi:[0,1]
	v_pk_add_f32 v[86:87], v[86:87], v[36:37] op_sel_hi:[1,0] neg_lo:[0,1] neg_hi:[0,1]
	v_pk_add_f32 v[70:71], v[70:71], v[36:37] op_sel_hi:[1,0] neg_lo:[0,1] neg_hi:[0,1]
	v_pk_add_f32 v[88:89], v[88:89], v[36:37] op_sel_hi:[1,0] neg_lo:[0,1] neg_hi:[0,1]
	v_pk_add_f32 v[72:73], v[72:73], v[36:37] op_sel_hi:[1,0] neg_lo:[0,1] neg_hi:[0,1]
	v_pk_add_f32 v[90:91], v[90:91], v[36:37] op_sel_hi:[1,0] neg_lo:[0,1] neg_hi:[0,1]
	v_pk_add_f32 v[74:75], v[74:75], v[36:37] op_sel_hi:[1,0] neg_lo:[0,1] neg_hi:[0,1]
	v_pk_add_f32 v[92:93], v[92:93], v[36:37] op_sel_hi:[1,0] neg_lo:[0,1] neg_hi:[0,1]
	v_pk_add_f32 v[76:77], v[76:77], v[36:37] op_sel_hi:[1,0] neg_lo:[0,1] neg_hi:[0,1]
	v_pk_add_f32 v[94:95], v[94:95], v[36:37] op_sel_hi:[1,0] neg_lo:[0,1] neg_hi:[0,1]
	v_pk_add_f32 v[78:79], v[78:79], v[36:37] op_sel_hi:[1,0] neg_lo:[0,1] neg_hi:[0,1]
	v_pk_add_f32 v[96:97], v[96:97], v[36:37] op_sel_hi:[1,0] neg_lo:[0,1] neg_hi:[0,1]
	v_pk_add_f32 v[80:81], v[80:81], v[36:37] op_sel_hi:[1,0] neg_lo:[0,1] neg_hi:[0,1]
	v_pk_mul_f32 v[32:33], v[32:33], v[38:39] op_sel_hi:[1,0]
	v_pk_mul_f32 v[30:31], v[30:31], v[38:39] op_sel_hi:[1,0]
	v_pk_mul_f32 v[28:29], v[28:29], v[38:39] op_sel_hi:[1,0]
	v_pk_mul_f32 v[26:27], v[26:27], v[38:39] op_sel_hi:[1,0]
	v_pk_mul_f32 v[24:25], v[24:25], v[38:39] op_sel_hi:[1,0]
	v_pk_mul_f32 v[22:23], v[22:23], v[38:39] op_sel_hi:[1,0]
	v_pk_mul_f32 v[20:21], v[20:21], v[38:39] op_sel_hi:[1,0]
	v_pk_mul_f32 v[18:19], v[18:19], v[38:39] op_sel_hi:[1,0]
	v_pk_mul_f32 v[16:17], v[16:17], v[38:39] op_sel_hi:[1,0]
	v_pk_mul_f32 v[14:15], v[14:15], v[38:39] op_sel_hi:[1,0]
	v_pk_mul_f32 v[12:13], v[12:13], v[38:39] op_sel_hi:[1,0]
	v_pk_mul_f32 v[10:11], v[10:11], v[38:39] op_sel_hi:[1,0]
	v_pk_mul_f32 v[8:9], v[8:9], v[38:39] op_sel_hi:[1,0]
	v_pk_mul_f32 v[6:7], v[6:7], v[38:39] op_sel_hi:[1,0]
	v_pk_mul_f32 v[4:5], v[4:5], v[38:39] op_sel_hi:[1,0]
	v_pk_mul_f32 v[2:3], v[2:3], v[38:39] op_sel_hi:[1,0]
	v_mul_f32_e32 v128, v128, v38
	v_mov_b32_e32 v35, v34
	v_mov_b32_e32 v36, v34
	v_mov_b32_e32 v37, v34
	v_mov_b32_e32 v38, v34
	v_mov_b32_e32 v39, v34
	v_mov_b32_e32 v40, v34
	v_mov_b32_e32 v41, v34
	v_mov_b32_e32 v42, v34
	v_mov_b32_e32 v43, v34
	v_mov_b32_e32 v44, v34
	v_mov_b32_e32 v45, v34
	v_mov_b32_e32 v46, v34
	v_mov_b32_e32 v47, v34
	v_mov_b32_e32 v48, v34
	v_mov_b32_e32 v49, v34
	v_mov_b32_e32 v50, v34
	v_mov_b32_e32 v51, v34
	v_mov_b32_e32 v52, v34
	v_mov_b32_e32 v53, v34
	v_mov_b32_e32 v54, v34
	v_mov_b32_e32 v55, v34
	v_mov_b32_e32 v56, v34
	v_mov_b32_e32 v57, v34
	v_mov_b32_e32 v58, v34
	v_mov_b32_e32 v59, v34
	v_mov_b32_e32 v60, v34
	v_mov_b32_e32 v61, v34
	v_mov_b32_e32 v62, v34
	v_mov_b32_e32 v63, v34
	v_mov_b32_e32 v64, v34
	v_mov_b32_e32 v65, v34
	s_branch .LBB0_402
.LBB0_401:
.LBB0_402:
	v_exp_f32_e32 v129, v82
	s_setprio 0
	v_exp_f32_e32 v146, v83
	v_exp_f32_e32 v147, v84
	v_exp_f32_e32 v148, v85
	v_exp_f32_e32 v149, v86
	v_exp_f32_e32 v150, v87
	v_exp_f32_e32 v151, v88
	v_exp_f32_e32 v152, v89
	v_exp_f32_e32 v153, v90
	v_exp_f32_e32 v154, v91
	v_exp_f32_e32 v155, v92
	v_exp_f32_e32 v156, v93
	v_exp_f32_e32 v157, v94
	v_exp_f32_e32 v158, v95
	v_exp_f32_e32 v159, v96
	v_exp_f32_e32 v160, v97
	s_add_i32 s58, s55, 4
	s_and_b32 s59, s56, 0xf00000
	s_and_b32 s58, s58, 3
	s_lshl_b32 s78, s59, 1
	s_mul_i32 s58, s58, 0x38000
	s_mov_b32 s59, s79
	s_add_u32 s98, s78, s58
	s_addc_u32 s99, s79, s79
	s_add_i32 s60, s57, s5
	v_lshl_add_u64 v[82:83], v[116:117], 0, s[98:99]
	s_mov_b32 m0, s60
	s_waitcnt vmcnt(0)
	s_barrier
	s_setprio 3
	v_add_u32_e32 v142, s54, v126
	ds_read_b128 v[130:133], v142
	ds_read_b128 v[134:137], v142 offset:2048
	global_load_lds_dwordx4 v[82:83], off
	v_lshl_add_u64 v[82:83], v[118:119], 0, s[98:99]
	s_add_i32 m0, s60, 0x2000
	s_nop 0
	global_load_lds_dwordx4 v[82:83], off
	v_exp_f32_e32 v161, v66
	v_exp_f32_e32 v162, v67
	v_exp_f32_e32 v163, v68
	v_exp_f32_e32 v164, v69
	ds_read_b128 v[66:69], v142 offset:4096
	v_exp_f32_e32 v165, v70
	v_exp_f32_e32 v166, v71
	s_waitcnt lgkmcnt(0)
	v_mfma_f32_32x32x16_bf16 v[82:97], v[130:133], v[110:113], v[50:65]
	v_exp_f32_e32 v167, v72
	v_exp_f32_e32 v168, v73
	ds_read_b128 v[70:73], v142 offset:6144
	v_exp_f32_e32 v169, v74
	v_exp_f32_e32 v170, v75
	v_exp_f32_e32 v171, v76
	v_exp_f32_e32 v172, v77
	v_mfma_f32_32x32x16_bf16 v[82:97], v[134:137], v[106:109], v[82:97]
	ds_read_b128 v[130:133], v142 offset:512
	ds_read_b128 v[134:137], v142 offset:2560
	ds_read_b128 v[138:141], v142 offset:4608
	ds_read_b128 v[142:145], v142 offset:6656
	v_exp_f32_e32 v173, v78
	v_exp_f32_e32 v174, v79
	v_exp_f32_e32 v175, v80
	v_exp_f32_e32 v176, v81
	v_mfma_f32_32x32x16_bf16 v[82:97], v[66:69], v[102:105], v[82:97]
	v_add_f32_e32 v66, v129, v146
	v_add_f32_e32 v66, v147, v66
	v_add_f32_e32 v66, v148, v66
	v_add_f32_e32 v66, v149, v66
	v_add_f32_e32 v66, v150, v66
	v_add_f32_e32 v66, v151, v66
	v_add_f32_e32 v66, v152, v66
	v_add_f32_e32 v66, v153, v66
	s_waitcnt lgkmcnt(0)
	v_mfma_f32_32x32x16_bf16 v[82:97], v[70:73], v[98:101], v[82:97]
	v_add_f32_e32 v177, v154, v66
	v_mfma_f32_32x32x16_bf16 v[66:81], v[130:133], v[110:113], v[50:65]
	v_add_f32_e32 v130, v155, v177
	v_add_f32_e32 v130, v156, v130
	v_add_f32_e32 v130, v157, v130
	v_add_f32_e32 v130, v158, v130
	v_add_f32_e32 v130, v159, v130
	v_add_f32_e32 v130, v160, v130
	v_add_f32_e32 v130, v161, v130
	v_mfma_f32_32x32x16_bf16 v[66:81], v[134:137], v[106:109], v[66:81]
	v_add_f32_e32 v130, v162, v130
	v_add_f32_e32 v130, v163, v130
	v_add_f32_e32 v130, v164, v130
	v_add_f32_e32 v130, v165, v130
	v_add_f32_e32 v130, v166, v130
	v_add_f32_e32 v130, v167, v130
	s_setprio 2
	v_add_f32_e32 v130, v168, v130
	v_mfma_f32_32x32x16_bf16 v[66:81], v[138:141], v[102:105], v[66:81]
	v_add_f32_e32 v130, v169, v130
	v_add_f32_e32 v130, v170, v130
	v_add_f32_e32 v130, v171, v130
	v_add_f32_e32 v130, v172, v130
	v_add_f32_e32 v130, v173, v130
	v_add_f32_e32 v130, v174, v130
	v_add_f32_e32 v177, v175, v130
	v_mfma_f32_32x32x16_bf16 v[66:81], v[142:145], v[98:101], v[66:81]
	v_cvt_pk_bf16_f32 v130, v129, v146
	v_cvt_pk_bf16_f32 v131, v147, v148
	v_cvt_pk_bf16_f32 v132, v149, v150
	v_cvt_pk_bf16_f32 v133, v151, v152
	v_cvt_pk_bf16_f32 v134, v153, v154
	v_cvt_pk_bf16_f32 v135, v155, v156
	v_cvt_pk_bf16_f32 v136, v157, v158
	v_cvt_pk_bf16_f32 v137, v159, v160
	v_cvt_pk_bf16_f32 v138, v161, v162
	v_cvt_pk_bf16_f32 v139, v163, v164
	v_cvt_pk_bf16_f32 v140, v165, v166
	v_cvt_pk_bf16_f32 v141, v167, v168
	v_cvt_pk_bf16_f32 v142, v169, v170
	v_cvt_pk_bf16_f32 v143, v171, v172
	v_cvt_pk_bf16_f32 v144, v173, v174
	v_cvt_pk_bf16_f32 v145, v175, v176
	v_add_u32_e32 v129, s53, v125
	ds_read_b64_tr_b16 v[146:147], v129 offset:8192
	ds_read_b64_tr_b16 v[148:149], v129 offset:8704
	ds_read_b64_tr_b16 v[150:151], v129 offset:12288
	s_waitcnt lgkmcnt(1)
	v_mfma_f32_32x32x16_bf16 v[18:33], v[146:149], v[130:133], v[18:33]
	ds_read_b64_tr_b16 v[152:153], v129 offset:12800
	ds_read_b64_tr_b16 v[146:147], v129 offset:9216
	s_waitcnt lgkmcnt(1)
	v_mfma_f32_32x32x16_bf16 v[2:17], v[150:153], v[130:133], v[2:17]
	ds_read_b64_tr_b16 v[148:149], v129 offset:9728
	ds_read_b64_tr_b16 v[130:131], v129 offset:13312
	s_waitcnt lgkmcnt(1)
	v_mfma_f32_32x32x16_bf16 v[18:33], v[146:149], v[134:137], v[18:33]
	ds_read_b64_tr_b16 v[132:133], v129 offset:13824
	ds_read_b64_tr_b16 v[146:147], v129 offset:10240
	s_waitcnt lgkmcnt(1)
	v_mfma_f32_32x32x16_bf16 v[2:17], v[130:133], v[134:137], v[2:17]
	ds_read_b64_tr_b16 v[148:149], v129 offset:10752
	ds_read_b64_tr_b16 v[130:131], v129 offset:11264
	ds_read_b64_tr_b16 v[132:133], v129 offset:11776
	ds_read_b64_tr_b16 v[134:135], v129 offset:14336
	ds_read_b64_tr_b16 v[136:137], v129 offset:14848
	ds_read_b64_tr_b16 v[150:151], v129 offset:15360
	ds_read_b64_tr_b16 v[152:153], v129 offset:15872
	v_max_f32_e32 v129, v67, v67
	s_waitcnt lgkmcnt(6)
	v_mfma_f32_32x32x16_bf16 v[18:33], v[146:149], v[138:141], v[18:33]
	v_max_f32_e32 v146, v83, v83
	v_max_f32_e32 v129, v146, v129
	v_max3_f32 v146, v82, v66, v84
	v_max3_f32 v129, v129, v85, v69
	v_max3_f32 v146, v146, v68, v86
	v_max3_f32 v129, v129, v87, v71
	v_max3_f32 v129, v129, v89, v73
	s_waitcnt lgkmcnt(2)
	s_setprio 1
	v_mfma_f32_32x32x16_bf16 v[2:17], v[134:137], v[138:141], v[2:17]
	v_max3_f32 v134, v146, v70, v88
	v_max3_f32 v134, v134, v72, v90
	v_max3_f32 v129, v129, v91, v75
	v_max3_f32 v134, v134, v74, v92
	v_max3_f32 v129, v129, v93, v77
	v_max3_f32 v134, v134, v76, v94
	v_max3_f32 v129, v129, v95, v79
	v_mfma_f32_32x32x16_bf16 v[18:33], v[130:133], v[142:145], v[18:33]
	v_max3_f32 v130, v134, v78, v96
	v_max3_f32 v129, v129, v97, v81
	v_add_f32_e32 v131, v176, v177
	v_max3_f32 v129, v130, v80, v129
	v_add_f32_e32 v128, v128, v131
	v_cmp_lt_f32_e32 vcc, s33, v129
	s_waitcnt lgkmcnt(0)
	v_mfma_f32_32x32x16_bf16 v[2:17], v[150:153], v[142:145], v[2:17]
	s_cbranch_vccz .LBB0_404
	v_mov_b32_e32 v34, v129
	s_nop 1
	v_permlane32_swap_b32 v129, v34
	s_nop 1
	s_nop 0
	v_max3_f32 v36, v129, v34, 0
	v_exp_f32_e64 v38, -v36
	v_add_f32_e32 v127, v127, v36
	v_xor_b32_e32 v34, 0x80000000, v127
	v_pk_add_f32 v[82:83], v[82:83], v[36:37] op_sel_hi:[1,0] neg_lo:[0,1] neg_hi:[0,1]
	v_pk_add_f32 v[84:85], v[84:85], v[36:37] op_sel_hi:[1,0] neg_lo:[0,1] neg_hi:[0,1]
	v_pk_add_f32 v[86:87], v[86:87], v[36:37] op_sel_hi:[1,0] neg_lo:[0,1] neg_hi:[0,1]
	v_pk_add_f32 v[88:89], v[88:89], v[36:37] op_sel_hi:[1,0] neg_lo:[0,1] neg_hi:[0,1]
	v_pk_add_f32 v[90:91], v[90:91], v[36:37] op_sel_hi:[1,0] neg_lo:[0,1] neg_hi:[0,1]
	v_pk_add_f32 v[92:93], v[92:93], v[36:37] op_sel_hi:[1,0] neg_lo:[0,1] neg_hi:[0,1]
	v_pk_add_f32 v[94:95], v[94:95], v[36:37] op_sel_hi:[1,0] neg_lo:[0,1] neg_hi:[0,1]
	v_pk_add_f32 v[96:97], v[96:97], v[36:37] op_sel_hi:[1,0] neg_lo:[0,1] neg_hi:[0,1]
	v_sub_f32_e32 v81, v81, v36
	v_sub_f32_e32 v80, v80, v36
	v_sub_f32_e32 v79, v79, v36
	v_sub_f32_e32 v78, v78, v36
	v_sub_f32_e32 v77, v77, v36
	v_sub_f32_e32 v76, v76, v36
	v_sub_f32_e32 v75, v75, v36
	v_sub_f32_e32 v74, v74, v36
	v_sub_f32_e32 v73, v73, v36
	v_sub_f32_e32 v72, v72, v36
	v_sub_f32_e32 v71, v71, v36
	v_sub_f32_e32 v70, v70, v36
	v_sub_f32_e32 v69, v69, v36
	v_sub_f32_e32 v68, v68, v36
	v_sub_f32_e32 v67, v67, v36
	v_sub_f32_e32 v66, v66, v36
	v_pk_mul_f32 v[32:33], v[32:33], v[38:39] op_sel_hi:[1,0]
	v_pk_mul_f32 v[30:31], v[30:31], v[38:39] op_sel_hi:[1,0]
	v_pk_mul_f32 v[28:29], v[28:29], v[38:39] op_sel_hi:[1,0]
	v_pk_mul_f32 v[26:27], v[26:27], v[38:39] op_sel_hi:[1,0]
	v_pk_mul_f32 v[24:25], v[24:25], v[38:39] op_sel_hi:[1,0]
	v_pk_mul_f32 v[22:23], v[22:23], v[38:39] op_sel_hi:[1,0]
	v_pk_mul_f32 v[20:21], v[20:21], v[38:39] op_sel_hi:[1,0]
	v_pk_mul_f32 v[18:19], v[18:19], v[38:39] op_sel_hi:[1,0]
	v_pk_mul_f32 v[16:17], v[16:17], v[38:39] op_sel_hi:[1,0]
	v_pk_mul_f32 v[14:15], v[14:15], v[38:39] op_sel_hi:[1,0]
	v_pk_mul_f32 v[12:13], v[12:13], v[38:39] op_sel_hi:[1,0]
	v_pk_mul_f32 v[10:11], v[10:11], v[38:39] op_sel_hi:[1,0]
	v_pk_mul_f32 v[8:9], v[8:9], v[38:39] op_sel_hi:[1,0]
	v_pk_mul_f32 v[6:7], v[6:7], v[38:39] op_sel_hi:[1,0]
	v_pk_mul_f32 v[4:5], v[4:5], v[38:39] op_sel_hi:[1,0]
	v_pk_mul_f32 v[2:3], v[2:3], v[38:39] op_sel_hi:[1,0]
	v_mul_f32_e32 v128, v128, v38
	v_mov_b32_e32 v35, v34
	v_mov_b32_e32 v36, v34
	v_mov_b32_e32 v37, v34
	v_mov_b32_e32 v38, v34
	v_mov_b32_e32 v39, v34
	v_mov_b32_e32 v40, v34
	v_mov_b32_e32 v41, v34
	v_mov_b32_e32 v42, v34
	v_mov_b32_e32 v43, v34
	v_mov_b32_e32 v44, v34
	v_mov_b32_e32 v45, v34
	v_mov_b32_e32 v46, v34
	v_mov_b32_e32 v47, v34
	v_mov_b32_e32 v48, v34
	v_mov_b32_e32 v49, v34
	v_mov_b32_e32 v50, v34
	v_mov_b32_e32 v51, v34
	v_mov_b32_e32 v52, v34
	v_mov_b32_e32 v53, v34
	v_mov_b32_e32 v54, v34
	v_mov_b32_e32 v55, v34
	v_mov_b32_e32 v56, v34
	v_mov_b32_e32 v57, v34
	v_mov_b32_e32 v58, v34
	v_mov_b32_e32 v59, v34
	v_mov_b32_e32 v60, v34
	v_mov_b32_e32 v61, v34
	v_mov_b32_e32 v62, v34
	v_mov_b32_e32 v63, v34
	v_mov_b32_e32 v64, v34
	v_mov_b32_e32 v65, v34

	.amdhsa_kernel _Z10fwd_kernel4Args
		.amdhsa_group_segment_fixed_size 0
		.amdhsa_private_segment_fixed_size 0
		.amdhsa_kernarg_size 400
		.amdhsa_user_sgpr_count 2
		.amdhsa_user_sgpr_dispatch_ptr 0
		.amdhsa_user_sgpr_queue_ptr 0
		.amdhsa_user_sgpr_kernarg_segment_ptr 1
		.amdhsa_user_sgpr_dispatch_id 0
		.amdhsa_user_sgpr_kernarg_preload_length 0
		.amdhsa_user_sgpr_kernarg_preload_offset 0
		.amdhsa_user_sgpr_private_segment_size 0
		.amdhsa_uses_dynamic_stack 0
		.amdhsa_enable_private_segment 0
		.amdhsa_system_sgpr_workgroup_id_x 1
		.amdhsa_system_sgpr_workgroup_id_y 0
		.amdhsa_system_sgpr_workgroup_id_z 0
		.amdhsa_system_sgpr_workgroup_info 0
		.amdhsa_system_vgpr_workitem_id 2
		.amdhsa_next_free_vgpr 240
		.amdhsa_next_free_sgpr 102
		.amdhsa_accum_offset 240
		.amdhsa_reserve_vcc 1
		.amdhsa_float_round_mode_32 0
		.amdhsa_float_round_mode_16_64 0
		.amdhsa_float_denorm_mode_32 3
		.amdhsa_float_denorm_mode_16_64 3
		.amdhsa_dx10_clamp 1
		.amdhsa_ieee_mode 1
		.amdhsa_fp16_overflow 0
		.amdhsa_tg_split 0
		.amdhsa_exception_fp_ieee_invalid_op 0
		.amdhsa_exception_fp_denorm_src 0
		.amdhsa_exception_fp_ieee_div_zero 0
		.amdhsa_exception_fp_ieee_overflow 0
		.amdhsa_exception_fp_ieee_underflow 0
		.amdhsa_exception_fp_ieee_inexact 0
		.amdhsa_exception_int_div_zero 0
	.end_amdhsa_kernel

amdhsa.kernels:
  - .agpr_count:     0
    .args:
      - .offset:         0
        .size:           144
        .value_kind:     by_value
      - .offset:         144
        .size:           4
        .value_kind:     hidden_block_count_x
      - .offset:         148
        .size:           4
        .value_kind:     hidden_block_count_y
      - .offset:         152
        .size:           4
        .value_kind:     hidden_block_count_z
      - .offset:         156
        .size:           2
        .value_kind:     hidden_group_size_x
      - .offset:         158
        .size:           2
        .value_kind:     hidden_group_size_y
      - .offset:         160
        .size:           2
        .value_kind:     hidden_group_size_z
      - .offset:         162
        .size:           2
        .value_kind:     hidden_remainder_x
      - .offset:         164
        .size:           2
        .value_kind:     hidden_remainder_y
      - .offset:         166
        .size:           2
        .value_kind:     hidden_remainder_z
      - .offset:         184
        .size:           8
        .value_kind:     hidden_global_offset_x
      - .offset:         192
        .size:           8
        .value_kind:     hidden_global_offset_y
      - .offset:         200
        .size:           8
        .value_kind:     hidden_global_offset_z
      - .offset:         208
        .size:           2
        .value_kind:     hidden_grid_dims
      - .offset:         232
        .size:           8
        .value_kind:     hidden_multigrid_sync_arg
      - .offset:         264
        .size:           4
        .value_kind:     hidden_dynamic_lds_size
    .group_segment_fixed_size: 0
    .kernarg_segment_align: 8
    .kernarg_segment_size: 400
    .language:       OpenCL C
    .language_version:
      - 2
      - 0
    .max_flat_workgroup_size: 512
    .name:           _Z10fwd_kernel4Args
    .private_segment_fixed_size: 0
    .sgpr_count:     108
    .sgpr_spill_count: 216
    .symbol:         _Z10fwd_kernel4Args.kd
    .uniform_work_group_size: 1
    .uses_dynamic_stack: false
    .vgpr_count:     240
    .vgpr_spill_count: 0
    .wavefront_size: 64
